# norm phase prologue: the 12 modulation-vector loads issued back to back (1 round trip instead of 4)
# speedup vs baseline: 1.0094x; 1.0094x over previous
.LBB0_203:
	v_ashrrev_i32_e32 v33, 31, v32
	v_lshlrev_b64 v[2:3], 12, v[32:33]
	v_lshl_add_u64 v[44:45], v[34:35], 0, v[2:3]
	v_ashrrev_i32_e32 v2, 9, v25
	v_add_u32_e32 v4, s10, v2
	v_mov_b64_e32 v[2:3], s[2:3]
	v_mad_i64_i32 v[2:3], s[8:9], v4, s73, v[2:3]
	s_mov_b64 s[8:9], 0x1000
	s_nop 0
	v_lshl_add_u64 v[58:59], v[2:3], 0, s[8:9]
	v_lshl_add_u64 v[4:5], v[58:59], 0, v[0:1]
	v_mov_b32_e32 v37, v1
	v_mov_b32_e32 v39, v1
	v_mov_b32_e32 v41, v1
	v_lshl_add_u64 v[64:65], v[2:3], 0, v[0:1]
	global_load_dwordx4 v[70:73], v[4:5], off
	global_load_dwordx4 v[74:77], v[22:23], off
	global_load_dwordx4 v[2:5], v[64:65], off
	v_lshl_add_u64 v[6:7], v[58:59], 0, v[36:37]
	v_lshl_add_u64 v[10:11], v[58:59], 0, v[38:39]
	v_lshl_add_u64 v[14:15], v[58:59], 0, v[40:41]
	global_load_dwordx4 v[78:81], v[6:7], off
	global_load_dwordx4 v[82:85], v[22:23], off offset:1024
	global_load_dwordx4 v[6:9], v[64:65], off offset:1024
	global_load_dwordx4 v[112:115], v[10:11], off
	global_load_dwordx4 v[116:119], v[22:23], off offset:2048
	global_load_dwordx4 v[10:13], v[64:65], off offset:2048
	global_load_dwordx4 v[120:123], v[14:15], off
	global_load_dwordx4 v[124:127], v[22:23], off offset:3072
	global_load_dwordx4 v[14:17], v[64:65], off offset:3072
	v_lshlrev_b64 v[42:43], 4, v[32:33]
	s_mov_b64 s[8:9], 0
	s_waitcnt vmcnt(10)
	v_pk_add_f32 v[70:71], v[70:71], 1.0 op_sel_hi:[1,0]
	v_pk_add_f32 v[72:73], v[72:73], 1.0 op_sel_hi:[1,0]
	v_pk_mul_f32 v[48:49], v[74:75], v[70:71]
	v_pk_mul_f32 v[46:47], v[76:77], v[72:73]
	s_waitcnt vmcnt(7)
	v_pk_add_f32 v[78:79], v[78:79], 1.0 op_sel_hi:[1,0]
	v_pk_add_f32 v[80:81], v[80:81], 1.0 op_sel_hi:[1,0]
	v_pk_mul_f32 v[52:53], v[82:83], v[78:79]
	v_pk_mul_f32 v[50:51], v[84:85], v[80:81]
	s_waitcnt vmcnt(4)
	v_pk_add_f32 v[112:113], v[112:113], 1.0 op_sel_hi:[1,0]
	v_pk_add_f32 v[114:115], v[114:115], 1.0 op_sel_hi:[1,0]
	v_pk_mul_f32 v[56:57], v[116:117], v[112:113]
	v_pk_mul_f32 v[54:55], v[118:119], v[114:115]
	s_waitcnt vmcnt(1)
	v_pk_add_f32 v[120:121], v[120:121], 1.0 op_sel_hi:[1,0]
	v_pk_add_f32 v[122:123], v[122:123], 1.0 op_sel_hi:[1,0]
	v_pk_mul_f32 v[60:61], v[124:125], v[120:121]
	v_pk_mul_f32 v[58:59], v[126:127], v[122:123]
	v_mov_b32_e32 v62, v69
